# k12 plus: prologue x->bf16 rows rebalanced (the 64 workgroups that also build the S5 matrices take 10 rows per wave, the others 18, when the grid is 256)
# speedup vs baseline: 1.0134x; 1.0018x over previous
; __device__ __forceinline__ unsigned cvt_pk_bf16(float lo, float hi) { unsigned r; asm volatile("v_cvt_pk_bf16_f32 %0, %1, %2" : "=v"(r) : "v"(lo), "v"(hi)); return r; }
; #define GAS __attribute__((address_space(1)))
; __device__ __forceinline__ void p0_prologue(const In& in, float* out, unsigned char* ws, LAS unsigned char* lds, int tid, int lane, int wave) {
;     ...
;     { bf16* XB = (bf16*)(ws + WS_XB); float* ss1 = (float*)(ws + WS_STAT) + ST_SS1 * MROWS;
;       for (int mm = gw; mm < MROWS * P0_REP; mm += NGW) { const int m = mm % MROWS; const GAS f32x4* xr = (const GAS f32x4*)(in.x + (size_t)m * DM) + lane; GAS v2u* o = (GAS v2u*)(XB + (size_t)m * DM) + lane; float s = 0.f;
; #pragma unroll
;           for (int j = 0; j < 8; ++j) { const f32x4 v = xr[64 * j]; s += (v.x * v.x + v.y * v.y) + (v.z * v.z + v.w * v.w); v2u w; w.x = cvt_pk_bf16(v.x, v.y); w.y = cvt_pk_bf16(v.z, v.w); o[64 * j] = w; }
;           s = wave_sum(s); if (lane == 0) ss1[m] = s; } }
.Lxb_entry:
	s_mov_b64 s[0:1], exec
	v_lshlrev_b32_e32 v2, 4, v74
	v_lshlrev_b32_e32 v3, 3, v74
	v_mov_b32_e32 v4, 0
	v_mbcnt_hi_u32_b32 v5, -1, v254
	v_xor_b32_e32 v68, 1, v5
	v_xor_b32_e32 v69, 2, v5
	v_xor_b32_e32 v70, 4, v5
	v_xor_b32_e32 v71, 8, v5
	v_xor_b32_e32 v72, 16, v5
	v_xor_b32_e32 v73, 32, v5
	v_lshlrev_b32_e32 v68, 2, v68
	v_lshlrev_b32_e32 v69, 2, v69
	v_lshlrev_b32_e32 v70, 2, v70
	v_lshlrev_b32_e32 v71, 2, v71
	v_lshlrev_b32_e32 v72, 2, v72
	v_lshlrev_b32_e32 v73, 2, v73
	s_mov_b32 s6, s24
	s_mov_b32 s7, s26
	s_movk_i32 s10, 0x7fff
	s_cmpk_lg_u32 s70, 0x100
	s_cbranch_scc1 .Lxb_norm
	s_cmpk_lt_u32 s2, 64
	s_cbranch_scc0 .Lxb_big
	s_movk_i32 s7, 0x200
	s_movk_i32 s10, 0x13ff
	s_branch .Lxb_norm
.Lxb_big:
	s_add_i32 s6, s24, 0x1200
	s_movk_i32 s7, 0x600
.Lxb_norm:
	s_waitcnt lgkmcnt(0)
	s_lshl_b32 s3, s6, 13
	s_add_u32 s4, s52, s3
	s_addc_u32 s5, s53, 0
	s_add_u32 s4, s4, 0x1000
	s_addc_u32 s5, s5, 0
	global_load_dwordx4 v[16:19], v2, s[4:5] offset:-4096
	global_load_dwordx4 v[20:23], v2, s[4:5] offset:-3072
	global_load_dwordx4 v[24:27], v2, s[4:5] offset:-2048
	global_load_dwordx4 v[28:31], v2, s[4:5] offset:-1024
	global_load_dwordx4 v[32:35], v2, s[4:5] offset:0
	global_load_dwordx4 v[36:39], v2, s[4:5] offset:1024
	global_load_dwordx4 v[40:43], v2, s[4:5] offset:2048
	global_load_dwordx4 v[44:47], v2, s[4:5] offset:3072
	s_lshl_b32 s3, s6, 12
	s_add_u32 s8, s28, s3
	s_addc_u32 s9, s29, 0
	s_lshl_b32 s3, s6, 2
	s_add_u32 s12, s68, s3
	s_addc_u32 s13, s69, 0
	s_add_i32 s6, s6, s7
	s_cmp_gt_i32 s6, s10
	s_cbranch_scc1 .Lxb_last_f
	s_lshl_b32 s3, s6, 13
	s_add_u32 s4, s52, s3
	s_addc_u32 s5, s53, 0
	s_add_u32 s4, s4, 0x1000
	s_addc_u32 s5, s5, 0
	global_load_dwordx4 v[80:83], v2, s[4:5] offset:-4096
	global_load_dwordx4 v[84:87], v2, s[4:5] offset:-3072
	global_load_dwordx4 v[88:91], v2, s[4:5] offset:-2048
	global_load_dwordx4 v[92:95], v2, s[4:5] offset:-1024
	global_load_dwordx4 v[96:99], v2, s[4:5] offset:0
	global_load_dwordx4 v[100:103], v2, s[4:5] offset:1024
	global_load_dwordx4 v[104:107], v2, s[4:5] offset:2048
	global_load_dwordx4 v[108:111], v2, s[4:5] offset:3072
	s_waitcnt vmcnt(8)
	v_cvt_pk_bf16_f32 v48, v16, v17
	v_cvt_pk_bf16_f32 v49, v18, v19
	v_mul_f32_e32 v65, v17, v17
	v_mul_f32_e32 v66, v19, v19
	global_store_dwordx2 v3, v[48:49], s[8:9]
	v_fmac_f32_e32 v65, v16, v16
	v_fmac_f32_e32 v66, v18, v18
	v_add_f32_e32 v64, v65, v66
	v_cvt_pk_bf16_f32 v50, v20, v21
	v_cvt_pk_bf16_f32 v51, v22, v23
	v_mul_f32_e32 v65, v21, v21
	v_mul_f32_e32 v66, v23, v23
	global_store_dwordx2 v3, v[50:51], s[8:9] offset:512
	v_fmac_f32_e32 v65, v20, v20
	v_fmac_f32_e32 v66, v22, v22
	v_add_f32_e32 v65, v65, v66
	v_add_f32_e32 v64, v64, v65
	v_cvt_pk_bf16_f32 v52, v24, v25
	v_cvt_pk_bf16_f32 v53, v26, v27
	v_mul_f32_e32 v65, v25, v25
	v_mul_f32_e32 v66, v27, v27
	global_store_dwordx2 v3, v[52:53], s[8:9] offset:1024
	v_fmac_f32_e32 v65, v24, v24
	v_fmac_f32_e32 v66, v26, v26
	v_add_f32_e32 v65, v65, v66
	v_add_f32_e32 v64, v64, v65
	v_cvt_pk_bf16_f32 v54, v28, v29
	v_cvt_pk_bf16_f32 v55, v30, v31
	v_mul_f32_e32 v65, v29, v29
	v_mul_f32_e32 v66, v31, v31
	global_store_dwordx2 v3, v[54:55], s[8:9] offset:1536
	v_fmac_f32_e32 v65, v28, v28
	v_fmac_f32_e32 v66, v30, v30
	v_add_f32_e32 v65, v65, v66
	v_add_f32_e32 v64, v64, v65
	v_cvt_pk_bf16_f32 v56, v32, v33
	v_cvt_pk_bf16_f32 v57, v34, v35
	v_mul_f32_e32 v65, v33, v33
	v_mul_f32_e32 v66, v35, v35
	global_store_dwordx2 v3, v[56:57], s[8:9] offset:2048
	v_fmac_f32_e32 v65, v32, v32
	v_fmac_f32_e32 v66, v34, v34
	v_add_f32_e32 v65, v65, v66
	v_add_f32_e32 v64, v64, v65
	v_cvt_pk_bf16_f32 v58, v36, v37
	v_cvt_pk_bf16_f32 v59, v38, v39
	v_mul_f32_e32 v65, v37, v37
	v_mul_f32_e32 v66, v39, v39
	global_store_dwordx2 v3, v[58:59], s[8:9] offset:2560
	v_fmac_f32_e32 v65, v36, v36
	v_fmac_f32_e32 v66, v38, v38
	v_add_f32_e32 v65, v65, v66
	v_add_f32_e32 v64, v64, v65
	v_cvt_pk_bf16_f32 v60, v40, v41
	v_cvt_pk_bf16_f32 v61, v42, v43
	v_mul_f32_e32 v65, v41, v41
	v_mul_f32_e32 v66, v43, v43
	global_store_dwordx2 v3, v[60:61], s[8:9] offset:3072
	v_fmac_f32_e32 v65, v40, v40
	v_fmac_f32_e32 v66, v42, v42
	v_add_f32_e32 v65, v65, v66
	v_add_f32_e32 v64, v64, v65
	v_cvt_pk_bf16_f32 v62, v44, v45
	v_cvt_pk_bf16_f32 v63, v46, v47
	v_mul_f32_e32 v65, v45, v45
	v_mul_f32_e32 v66, v47, v47
	global_store_dwordx2 v3, v[62:63], s[8:9] offset:3584
	v_fmac_f32_e32 v65, v44, v44
	v_fmac_f32_e32 v66, v46, v46
	v_add_f32_e32 v65, v65, v66
	v_add_f32_e32 v64, v64, v65
	ds_bpermute_b32 v67, v68, v64
	s_waitcnt lgkmcnt(0)
	v_add_f32_e32 v64, v64, v67
	ds_bpermute_b32 v67, v69, v64
	s_waitcnt lgkmcnt(0)
	v_add_f32_e32 v64, v64, v67
	ds_bpermute_b32 v67, v70, v64
	s_waitcnt lgkmcnt(0)
	v_add_f32_e32 v64, v64, v67
	ds_bpermute_b32 v67, v71, v64
	s_waitcnt lgkmcnt(0)
	v_add_f32_e32 v64, v64, v67
	ds_bpermute_b32 v67, v72, v64
	s_waitcnt lgkmcnt(0)
	v_add_f32_e32 v64, v64, v67
	ds_bpermute_b32 v67, v73, v64
	s_waitcnt lgkmcnt(0)
	v_add_f32_e32 v64, v64, v67
	s_mov_b64 exec, 1
	global_store_dword v4, v64, s[12:13]
	s_mov_b64 exec, s[0:1]
	s_branch .Lxb_next_f

; __device__ __forceinline__ unsigned cvt_pk_bf16(float lo, float hi) { unsigned r; asm volatile("v_cvt_pk_bf16_f32 %0, %1, %2" : "=v"(r) : "v"(lo), "v"(hi)); return r; }
; #define GAS __attribute__((address_space(1)))
; __device__ __forceinline__ void p0_prologue(const In& in, float* out, unsigned char* ws, LAS unsigned char* lds, int tid, int lane, int wave) {
;     ...
;     { bf16* XB = (bf16*)(ws + WS_XB); float* ss1 = (float*)(ws + WS_STAT) + ST_SS1 * MROWS;
;       for (int mm = gw; mm < MROWS * P0_REP; mm += NGW) { const int m = mm % MROWS; const GAS f32x4* xr = (const GAS f32x4*)(in.x + (size_t)m * DM) + lane; GAS v2u* o = (GAS v2u*)(XB + (size_t)m * DM) + lane; float s = 0.f;
; #pragma unroll
;           for (int j = 0; j < 8; ++j) { const f32x4 v = xr[64 * j]; s += (v.x * v.x + v.y * v.y) + (v.z * v.z + v.w * v.w); v2u w; w.x = cvt_pk_bf16(v.x, v.y); w.y = cvt_pk_bf16(v.z, v.w); o[64 * j] = w; }
;           s = wave_sum(s); if (lane == 0) ss1[m] = s; } }
.Lxb_next_f:
.Lxb_loop:
	s_lshl_b32 s3, s6, 12
	s_add_u32 s8, s28, s3
	s_addc_u32 s9, s29, 0
	s_lshl_b32 s3, s6, 2
	s_add_u32 s12, s68, s3
	s_addc_u32 s13, s69, 0
	s_add_i32 s6, s6, s7
	s_cmp_gt_i32 s6, s10
	s_cbranch_scc1 .Lxb_last_b
	s_lshl_b32 s3, s6, 13
	s_add_u32 s4, s52, s3
	s_addc_u32 s5, s53, 0
	s_add_u32 s4, s4, 0x1000
	s_addc_u32 s5, s5, 0
	global_load_dwordx4 v[16:19], v2, s[4:5] offset:-4096
	global_load_dwordx4 v[20:23], v2, s[4:5] offset:-3072
	global_load_dwordx4 v[24:27], v2, s[4:5] offset:-2048
	global_load_dwordx4 v[28:31], v2, s[4:5] offset:-1024
	global_load_dwordx4 v[32:35], v2, s[4:5] offset:0
	global_load_dwordx4 v[36:39], v2, s[4:5] offset:1024
	global_load_dwordx4 v[40:43], v2, s[4:5] offset:2048
	global_load_dwordx4 v[44:47], v2, s[4:5] offset:3072
	s_waitcnt vmcnt(17)
	v_cvt_pk_bf16_f32 v48, v80, v81
	v_cvt_pk_bf16_f32 v49, v82, v83
	v_mul_f32_e32 v65, v81, v81
	v_mul_f32_e32 v66, v83, v83
	global_store_dwordx2 v3, v[48:49], s[8:9]
	v_fmac_f32_e32 v65, v80, v80
	v_fmac_f32_e32 v66, v82, v82
	v_add_f32_e32 v64, v65, v66
	v_cvt_pk_bf16_f32 v50, v84, v85
	v_cvt_pk_bf16_f32 v51, v86, v87
	v_mul_f32_e32 v65, v85, v85
	v_mul_f32_e32 v66, v87, v87
	global_store_dwordx2 v3, v[50:51], s[8:9] offset:512
	v_fmac_f32_e32 v65, v84, v84
	v_fmac_f32_e32 v66, v86, v86
	v_add_f32_e32 v65, v65, v66
	v_add_f32_e32 v64, v64, v65
	v_cvt_pk_bf16_f32 v52, v88, v89
	v_cvt_pk_bf16_f32 v53, v90, v91
	v_mul_f32_e32 v65, v89, v89
	v_mul_f32_e32 v66, v91, v91
	global_store_dwordx2 v3, v[52:53], s[8:9] offset:1024
	v_fmac_f32_e32 v65, v88, v88
	v_fmac_f32_e32 v66, v90, v90
	v_add_f32_e32 v65, v65, v66
	v_add_f32_e32 v64, v64, v65
	v_cvt_pk_bf16_f32 v54, v92, v93
	v_cvt_pk_bf16_f32 v55, v94, v95
	v_mul_f32_e32 v65, v93, v93
	v_mul_f32_e32 v66, v95, v95
	global_store_dwordx2 v3, v[54:55], s[8:9] offset:1536
	v_fmac_f32_e32 v65, v92, v92
	v_fmac_f32_e32 v66, v94, v94
	v_add_f32_e32 v65, v65, v66
	v_add_f32_e32 v64, v64, v65
	v_cvt_pk_bf16_f32 v56, v96, v97
	v_cvt_pk_bf16_f32 v57, v98, v99
	v_mul_f32_e32 v65, v97, v97
	v_mul_f32_e32 v66, v99, v99
	global_store_dwordx2 v3, v[56:57], s[8:9] offset:2048
	v_fmac_f32_e32 v65, v96, v96
	v_fmac_f32_e32 v66, v98, v98
	v_add_f32_e32 v65, v65, v66
	v_add_f32_e32 v64, v64, v65
	v_cvt_pk_bf16_f32 v58, v100, v101
	v_cvt_pk_bf16_f32 v59, v102, v103
	v_mul_f32_e32 v65, v101, v101
	v_mul_f32_e32 v66, v103, v103
	global_store_dwordx2 v3, v[58:59], s[8:9] offset:2560
	v_fmac_f32_e32 v65, v100, v100
	v_fmac_f32_e32 v66, v102, v102
	v_add_f32_e32 v65, v65, v66
	v_add_f32_e32 v64, v64, v65
	v_cvt_pk_bf16_f32 v60, v104, v105
	v_cvt_pk_bf16_f32 v61, v106, v107
	v_mul_f32_e32 v65, v105, v105
	v_mul_f32_e32 v66, v107, v107
	global_store_dwordx2 v3, v[60:61], s[8:9] offset:3072
	v_fmac_f32_e32 v65, v104, v104
	v_fmac_f32_e32 v66, v106, v106
	v_add_f32_e32 v65, v65, v66
	v_add_f32_e32 v64, v64, v65
	v_cvt_pk_bf16_f32 v62, v108, v109
	v_cvt_pk_bf16_f32 v63, v110, v111
	v_mul_f32_e32 v65, v109, v109
	v_mul_f32_e32 v66, v111, v111
	global_store_dwordx2 v3, v[62:63], s[8:9] offset:3584
	v_fmac_f32_e32 v65, v108, v108
	v_fmac_f32_e32 v66, v110, v110
	v_add_f32_e32 v65, v65, v66
	v_add_f32_e32 v64, v64, v65
	ds_bpermute_b32 v67, v68, v64
	s_waitcnt lgkmcnt(0)
	v_add_f32_e32 v64, v64, v67
	ds_bpermute_b32 v67, v69, v64
	s_waitcnt lgkmcnt(0)
	v_add_f32_e32 v64, v64, v67
	ds_bpermute_b32 v67, v70, v64
	s_waitcnt lgkmcnt(0)
	v_add_f32_e32 v64, v64, v67
	ds_bpermute_b32 v67, v71, v64
	s_waitcnt lgkmcnt(0)
	v_add_f32_e32 v64, v64, v67
	ds_bpermute_b32 v67, v72, v64
	s_waitcnt lgkmcnt(0)
	v_add_f32_e32 v64, v64, v67
	ds_bpermute_b32 v67, v73, v64
	s_waitcnt lgkmcnt(0)
	v_add_f32_e32 v64, v64, v67
	s_mov_b64 exec, 1
	global_store_dword v4, v64, s[12:13]
	s_mov_b64 exec, s[0:1]
	s_branch .Lxb_next_b

; __device__ __forceinline__ unsigned cvt_pk_bf16(float lo, float hi) { unsigned r; asm volatile("v_cvt_pk_bf16_f32 %0, %1, %2" : "=v"(r) : "v"(lo), "v"(hi)); return r; }
; #define GAS __attribute__((address_space(1)))
; __device__ __forceinline__ void p0_prologue(const In& in, float* out, unsigned char* ws, LAS unsigned char* lds, int tid, int lane, int wave) {
;     ...
;     { bf16* XB = (bf16*)(ws + WS_XB); float* ss1 = (float*)(ws + WS_STAT) + ST_SS1 * MROWS;
;       for (int mm = gw; mm < MROWS * P0_REP; mm += NGW) { const int m = mm % MROWS; const GAS f32x4* xr = (const GAS f32x4*)(in.x + (size_t)m * DM) + lane; GAS v2u* o = (GAS v2u*)(XB + (size_t)m * DM) + lane; float s = 0.f;
; #pragma unroll
;           for (int j = 0; j < 8; ++j) { const f32x4 v = xr[64 * j]; s += (v.x * v.x + v.y * v.y) + (v.z * v.z + v.w * v.w); v2u w; w.x = cvt_pk_bf16(v.x, v.y); w.y = cvt_pk_bf16(v.z, v.w); o[64 * j] = w; }
;           s = wave_sum(s); if (lane == 0) ss1[m] = s; } }
.Lxb_next_b:
	s_lshl_b32 s3, s6, 12
	s_add_u32 s8, s28, s3
	s_addc_u32 s9, s29, 0
	s_lshl_b32 s3, s6, 2
	s_add_u32 s12, s68, s3
	s_addc_u32 s13, s69, 0
	s_add_i32 s6, s6, s7
	s_cmp_gt_i32 s6, s10
	s_cbranch_scc1 .Lxb_last_a
	s_lshl_b32 s3, s6, 13
	s_add_u32 s4, s52, s3
	s_addc_u32 s5, s53, 0
	s_add_u32 s4, s4, 0x1000
	s_addc_u32 s5, s5, 0
	global_load_dwordx4 v[80:83], v2, s[4:5] offset:-4096
	global_load_dwordx4 v[84:87], v2, s[4:5] offset:-3072
	global_load_dwordx4 v[88:91], v2, s[4:5] offset:-2048
	global_load_dwordx4 v[92:95], v2, s[4:5] offset:-1024
	global_load_dwordx4 v[96:99], v2, s[4:5] offset:0
	global_load_dwordx4 v[100:103], v2, s[4:5] offset:1024
	global_load_dwordx4 v[104:107], v2, s[4:5] offset:2048
	global_load_dwordx4 v[108:111], v2, s[4:5] offset:3072
	s_waitcnt vmcnt(17)
	v_cvt_pk_bf16_f32 v48, v16, v17
	v_cvt_pk_bf16_f32 v49, v18, v19
	v_mul_f32_e32 v65, v17, v17
	v_mul_f32_e32 v66, v19, v19
	global_store_dwordx2 v3, v[48:49], s[8:9]
	v_fmac_f32_e32 v65, v16, v16
	v_fmac_f32_e32 v66, v18, v18
	v_add_f32_e32 v64, v65, v66
	v_cvt_pk_bf16_f32 v50, v20, v21
	v_cvt_pk_bf16_f32 v51, v22, v23
	v_mul_f32_e32 v65, v21, v21
	v_mul_f32_e32 v66, v23, v23
	global_store_dwordx2 v3, v[50:51], s[8:9] offset:512
	v_fmac_f32_e32 v65, v20, v20
	v_fmac_f32_e32 v66, v22, v22
	v_add_f32_e32 v65, v65, v66
	v_add_f32_e32 v64, v64, v65
	v_cvt_pk_bf16_f32 v52, v24, v25
	v_cvt_pk_bf16_f32 v53, v26, v27
	v_mul_f32_e32 v65, v25, v25
	v_mul_f32_e32 v66, v27, v27
	global_store_dwordx2 v3, v[52:53], s[8:9] offset:1024
	v_fmac_f32_e32 v65, v24, v24
	v_fmac_f32_e32 v66, v26, v26
	v_add_f32_e32 v65, v65, v66
	v_add_f32_e32 v64, v64, v65
	v_cvt_pk_bf16_f32 v54, v28, v29
	v_cvt_pk_bf16_f32 v55, v30, v31
	v_mul_f32_e32 v65, v29, v29
	v_mul_f32_e32 v66, v31, v31
	global_store_dwordx2 v3, v[54:55], s[8:9] offset:1536
	v_fmac_f32_e32 v65, v28, v28
	v_fmac_f32_e32 v66, v30, v30
	v_add_f32_e32 v65, v65, v66
	v_add_f32_e32 v64, v64, v65
	v_cvt_pk_bf16_f32 v56, v32, v33
	v_cvt_pk_bf16_f32 v57, v34, v35
	v_mul_f32_e32 v65, v33, v33
	v_mul_f32_e32 v66, v35, v35
	global_store_dwordx2 v3, v[56:57], s[8:9] offset:2048
	v_fmac_f32_e32 v65, v32, v32
	v_fmac_f32_e32 v66, v34, v34
	v_add_f32_e32 v65, v65, v66
	v_add_f32_e32 v64, v64, v65
	v_cvt_pk_bf16_f32 v58, v36, v37
	v_cvt_pk_bf16_f32 v59, v38, v39
	v_mul_f32_e32 v65, v37, v37
	v_mul_f32_e32 v66, v39, v39
	global_store_dwordx2 v3, v[58:59], s[8:9] offset:2560
	v_fmac_f32_e32 v65, v36, v36
	v_fmac_f32_e32 v66, v38, v38
	v_add_f32_e32 v65, v65, v66
	v_add_f32_e32 v64, v64, v65
	v_cvt_pk_bf16_f32 v60, v40, v41
	v_cvt_pk_bf16_f32 v61, v42, v43
	v_mul_f32_e32 v65, v41, v41
	v_mul_f32_e32 v66, v43, v43
	global_store_dwordx2 v3, v[60:61], s[8:9] offset:3072
	v_fmac_f32_e32 v65, v40, v40
	v_fmac_f32_e32 v66, v42, v42
	v_add_f32_e32 v65, v65, v66
	v_add_f32_e32 v64, v64, v65
	v_cvt_pk_bf16_f32 v62, v44, v45
	v_cvt_pk_bf16_f32 v63, v46, v47
	v_mul_f32_e32 v65, v45, v45
	v_mul_f32_e32 v66, v47, v47
	global_store_dwordx2 v3, v[62:63], s[8:9] offset:3584
	v_fmac_f32_e32 v65, v44, v44
	v_fmac_f32_e32 v66, v46, v46
	v_add_f32_e32 v65, v65, v66
	v_add_f32_e32 v64, v64, v65
	ds_bpermute_b32 v67, v68, v64
	s_waitcnt lgkmcnt(0)
	v_add_f32_e32 v64, v64, v67
	ds_bpermute_b32 v67, v69, v64
	s_waitcnt lgkmcnt(0)
	v_add_f32_e32 v64, v64, v67
	ds_bpermute_b32 v67, v70, v64
	s_waitcnt lgkmcnt(0)
	v_add_f32_e32 v64, v64, v67
	ds_bpermute_b32 v67, v71, v64
	s_waitcnt lgkmcnt(0)
	v_add_f32_e32 v64, v64, v67
	ds_bpermute_b32 v67, v72, v64
	s_waitcnt lgkmcnt(0)
	v_add_f32_e32 v64, v64, v67
	ds_bpermute_b32 v67, v73, v64
	s_waitcnt lgkmcnt(0)
	v_add_f32_e32 v64, v64, v67
	s_mov_b64 exec, 1
	global_store_dword v4, v64, s[12:13]
	s_mov_b64 exec, s[0:1]
	s_branch .Lxb_next_a
